# diff-attn: second V-half unit reuses the row reference and row sums of its sibling (same scores), its steady-state loop drops the row-max chain, rescale test and row-sum adds
# speedup vs baseline: 1.0075x; 1.0075x over previous
; #define WAIT_BAR(N) asm volatile("s_waitcnt vmcnt(" #N ") lgkmcnt(0)\n\ts_barrier":::"memory")
;   #define DMA_K(t,slot) glds16(ksrc+(long)(t)*KVBLK*PQ,(unsigned)__builtin_amdgcn_readfirstlane(kdst+(slot)))
;   #define DMA_V(t,slot) glds16(vsrc+(long)(t)*KVBLK*PQ,(unsigned)__builtin_amdgcn_readfirstlane(vdst+(slot)))
;   #define CMASK(P0,P1,t) do{int jb_=(t)-(NT-4); if(jb_>=-2)cmask(P0,P1,jb_,qrel,hi,tab);}while(0)
;   #define START(P0,P1) do{ const float rm=rowmax(P0,P1); resc=false; \
;     { const float dl=rm; mhat=fadd_s(mhat,dl); \
;       _Pragma("unroll") for(int r=0;r<16;++r){P0[r]=fsub_s(P0[r],dl);P1[r]=fsub_s(P1[r],dl);} \
;       _Pragma("unroll") for(int r=0;r<16;++r)negm[r]=-mhat; asm volatile("":"+v"(negm)); } \
;     _Pragma("unroll") for(int r=0;r<16;++r)P0[r]=__builtin_amdgcn_exp2f(P0[r]); }while(0)
;   #define ROT() do{sl_prev=sl_cur;sl_cur=sl_next;sl_next=(sl_next==(NSLOT-1)*SLOTB)?0:sl_next+SLOTB;}while(0)
;   #define CMASK(P0,P1,t) do{}while(0)
;   #define CMASK(P0,P1,t) do{int jb_=(t)-(NT-4); if(jb_>=-2)cmask(P0,P1,jb_,qrel,hi,tab);}while(0)
; template<int THRL> __device__ __forceinline__ void attn_unit(int b,int qb,const bf16*Q,const bf16*__restrict__ K,const bf16*__restrict__ V,bf16*O,const __attribute__((address_space(3))) float*tab,char*shm){
;     ...
;   float mhat=0.f,l_reg=0.f;f32x16 o[2];o[0]=f32x16{};o[1]=f32x16{};f32x16 negm=f32x16{};asm volatile("":"+v"(negm));
;   const int qrel=wid*QBLK+r32;
;     ...
;   bool resc=false;
;     ...
;   f32x16 pA0,pA1,pB0,pB1;
;   int sl_prev=0,sl_cur=0,sl_next=SLOTB;
;     ...
;   DMA_K(2,2*SLOTB);
;   WAIT_BAR(3);
;   qkt(pA0,pA1,Kbase,qr,negm,r32,hi);asm volatile("s_nop 15\n\ts_nop 7":"+v"(pA0),"+v"(pA1));CMASK(pA0,pA1,0);
;   START(pA0,pA1);
;   _Pragma("unroll") for(int r=0;r<16;++r)pA1[r]=__builtin_amdgcn_exp2f(pA1[r]);
;   WAIT_BAR(0);
;   DMA_K(3,0);DMA_V(1,SLOTB);
;   ROT();
;   kload8(kf,kp0+sl_cur);
;   WAIT_BAR(2);
.LBB0_373:
	v_lshlrev_b32_e32 v0, 1, v34
	v_and_b32_e32 v227, 32, v0
	v_lshlrev_b32_e32 v0, 4, v34
	v_and_b32_e32 v0, 0xc0, v0
	v_lshl_or_b32 v226, v223, 8, v0
	v_add_u32_e32 v0, 0, v227
	v_add3_u32 v232, v0, v224, v226
	v_max3_f32 v0, v18, v19, v2
	v_max3_f32 v34, v20, v21, v3
	s_and_b32 s7, s7, 0x3fffffc0
	v_max3_f32 v0, v0, v4, v5
	v_max3_f32 v34, v34, v24, v25
	s_lshl_b32 s7, s7, 2
	v_max3_f32 v0, v0, v22, v23
	v_max3_f32 v34, v34, v8, v9
	s_add_i32 s29, s7, 0
	v_max3_f32 v0, v0, v6, v7
	v_max3_f32 v34, v34, v28, v29
	s_cmp_lg_u32 0, -1
	v_max3_f32 v0, v0, v26, v27
	v_max3_f32 v34, v34, v12, v13
	s_mov_b32 s12, 1
	v_max3_f32 v0, v0, v10, v11
	v_max3_f32 v34, v34, v32, v33
	s_mov_b32 s86, 0
	v_max3_f32 v0, v0, v30, v31
	v_max3_f32 v34, v34, v16, v17
	v_lshlrev_b32_e32 v233, 4, v223
	v_max3_f32 v0, v0, v14, v15
	v_lshl_add_u32 v228, v222, 2, s29
	v_max_f32_e32 v0, v0, v34
	s_nop 0
	v_mov_b32_e32 v34, v0
	s_nop 1
	v_permlane32_swap_b32_e32 v0, v34
	v_max_f32_e32 v0, v0, v34
	s_nop 0
	s_bitcmp1_b32 s46, 0
	s_cbranch_scc0 .Lj0_start
	v_mov_b32_e32 v0, v238
.Lj0_start:
	v_add_f32_e32 v229, v1, v0
	v_sub_f32_e32 v2, v2, v0
	v_sub_f32_e32 v3, v3, v0
	v_sub_f32_e32 v18, v18, v0
	v_sub_f32_e32 v19, v19, v0
	v_sub_f32_e32 v20, v20, v0
	s_nop 0
	v_xor_b32_e32 v48, 0x80000000, v229
	v_mov_b32_e32 v49, v48
	v_mov_b32_e32 v50, v48
	v_mov_b32_e32 v51, v48
	v_mov_b32_e32 v52, v48
	v_mov_b32_e32 v53, v48
	v_mov_b32_e32 v54, v48
	v_mov_b32_e32 v55, v48
	v_mov_b32_e32 v56, v48
	v_mov_b32_e32 v57, v48
	v_mov_b32_e32 v58, v48
	v_mov_b32_e32 v59, v48
	v_mov_b32_e32 v60, v48
	v_mov_b32_e32 v61, v48
	v_mov_b32_e32 v62, v48
	v_mov_b32_e32 v63, v48
	s_waitcnt vmcnt(0) lgkmcnt(0)
	s_barrier
	v_exp_f32_e32 v64, v2
	v_exp_f32_e32 v65, v3
	v_lshl_add_u64 v[2:3], v[204:205], 0, s[36:37]
	s_mov_b32 s7, m0
	s_mov_b32 m0, s97
	s_nop 0
	global_load_lds_dwordx4 v[2:3], off
	s_mov_b32 m0, s7
	s_cselect_b32 s7, 0, 0
	s_add_i32 s6, s7, s6
	v_lshl_add_u64 v[2:3], v[212:213], 0, s[22:23]
	s_add_i32 s6, s6, 0x8000
	s_mov_b32 s7, m0
	s_mov_b32 m0, s6
	s_nop 0
	global_load_lds_dwordx4 v[2:3], off
	s_mov_b32 m0, s7
	ds_read_b128 v[188:191], v231 offset:8192
	ds_read_b128 v[184:187], v231 offset:8704
	ds_read_b128 v[180:183], v231 offset:10240
	ds_read_b128 v[176:179], v231 offset:10752
	ds_read_b128 v[172:175], v231 offset:12288
	ds_read_b128 v[168:171], v231 offset:12800
	ds_read_b128 v[164:167], v231 offset:14336
	ds_read_b128 v[160:163], v231 offset:14848
	v_sub_f32_e32 v4, v4, v0
	v_sub_f32_e32 v21, v21, v0
	v_sub_f32_e32 v5, v5, v0
	v_sub_f32_e32 v22, v22, v0
	v_sub_f32_e32 v6, v6, v0
	v_sub_f32_e32 v23, v23, v0
	v_sub_f32_e32 v7, v7, v0
	v_sub_f32_e32 v24, v24, v0
	v_sub_f32_e32 v8, v8, v0
	v_sub_f32_e32 v25, v25, v0
	v_sub_f32_e32 v9, v9, v0
	v_sub_f32_e32 v26, v26, v0
	v_sub_f32_e32 v10, v10, v0
	v_sub_f32_e32 v27, v27, v0
	v_sub_f32_e32 v11, v11, v0
	v_sub_f32_e32 v28, v28, v0
	v_sub_f32_e32 v12, v12, v0
	v_sub_f32_e32 v29, v29, v0
	v_sub_f32_e32 v13, v13, v0
	v_sub_f32_e32 v30, v30, v0
	v_sub_f32_e32 v14, v14, v0
	v_sub_f32_e32 v31, v31, v0
	v_sub_f32_e32 v15, v15, v0
	v_sub_f32_e32 v32, v32, v0
	v_sub_f32_e32 v16, v16, v0
	v_sub_f32_e32 v33, v33, v0
	v_sub_f32_e32 v0, v17, v0
	v_exp_f32_e32 v80, v18
	v_exp_f32_e32 v81, v19
	v_exp_f32_e32 v82, v20
	v_exp_f32_e32 v83, v21
	v_exp_f32_e32 v84, v22
	v_exp_f32_e32 v85, v23
	v_exp_f32_e32 v86, v24
	v_exp_f32_e32 v87, v25
	v_exp_f32_e32 v88, v26
	v_exp_f32_e32 v89, v27
	v_exp_f32_e32 v90, v28
	v_exp_f32_e32 v91, v29
	v_exp_f32_e32 v92, v30
	v_exp_f32_e32 v93, v31
	v_exp_f32_e32 v94, v32
	v_exp_f32_e32 v95, v33
	v_exp_f32_e32 v66, v4
	v_exp_f32_e32 v67, v5
	v_exp_f32_e32 v68, v6
	v_exp_f32_e32 v69, v7
	v_exp_f32_e32 v70, v8
	v_exp_f32_e32 v71, v9
	v_exp_f32_e32 v72, v10
	v_exp_f32_e32 v73, v11
	v_exp_f32_e32 v74, v12
	v_exp_f32_e32 v75, v13
	v_exp_f32_e32 v76, v14
	v_exp_f32_e32 v77, v15
	v_exp_f32_e32 v78, v16
	v_exp_f32_e32 v79, v0
	s_waitcnt vmcnt(2) lgkmcnt(0)
	s_barrier
	s_andn2_b64 vcc, exec, s[80:81]
	v_cmp_gt_u32_e64 s[6:7], 32, v220
	s_cbranch_vccnz .LBB0_389
	v_mov_b32_e32 v14, v1
	v_mov_b32_e32 v15, v1
	v_mov_b32_e32 v0, v1
	v_mov_b32_e32 v2, v1
	v_mov_b32_e32 v3, v1
	v_mov_b32_e32 v4, v1
	v_mov_b32_e32 v5, v1
	v_mov_b32_e32 v6, v1
	v_mov_b32_e32 v7, v1
	v_mov_b32_e32 v8, v1
	v_mov_b32_e32 v9, v1
	v_mov_b32_e32 v10, v1
	v_mov_b32_e32 v11, v1
	v_mov_b32_e32 v12, v1
	v_mov_b32_e32 v13, v1
	v_mov_b64_e32 v[46:47], v[14:15]
	v_mov_b64_e32 v[30:31], v[14:15]
	v_lshl_add_u64 v[196:197], v[212:213], 0, s[36:37]
	v_lshl_add_u64 v[198:199], v[204:205], 0, s[38:39]
	s_mov_b32 s8, 0
	s_movk_i32 s86, 0x4000
	s_movk_i32 s87, 0x2000
	v_mov_b32_e32 v234, 0
	s_mov_b32 s12, 8
	v_mov_b64_e32 v[44:45], v[12:13]
	v_mov_b64_e32 v[42:43], v[10:11]
	v_mov_b64_e32 v[40:41], v[8:9]
	v_mov_b64_e32 v[38:39], v[6:7]
	v_mov_b64_e32 v[36:37], v[4:5]
	v_mov_b64_e32 v[34:35], v[2:3]
	v_mov_b64_e32 v[32:33], v[0:1]
	v_mov_b64_e32 v[28:29], v[12:13]
	v_mov_b64_e32 v[26:27], v[10:11]
	v_mov_b64_e32 v[24:25], v[8:9]
	v_mov_b64_e32 v[22:23], v[6:7]
	v_mov_b64_e32 v[20:21], v[4:5]
	v_mov_b64_e32 v[18:19], v[2:3]
	v_mov_b64_e32 v[16:17], v[0:1]
	s_bitcmp1_b32 s46, 0
	s_cbranch_scc1 .Lj1_375

.Lj1_375:
	v_add_u32_e32 v0, s8, v232
	ds_read_b64_tr_b16 v[192:193], v0 offset:24576
	ds_read_b64_tr_b16 v[194:195], v0 offset:25088
	s_waitcnt lgkmcnt(9)
	v_mfma_f32_32x32x16_bf16 v[112:127], v[188:191], v[156:159], v[48:63]
	v_cvt_pk_bf16_f32 v140, v80, v81
	v_cvt_pk_bf16_f32 v141, v82, v83
	ds_read_b64_tr_b16 v[80:81], v0 offset:28672
	ds_read_b64_tr_b16 v[82:83], v0 offset:29184
	s_waitcnt lgkmcnt(10)
	v_mfma_f32_32x32x16_bf16 v[96:111], v[184:187], v[156:159], v[48:63]
	v_cvt_pk_bf16_f32 v142, v84, v85
	v_cvt_pk_bf16_f32 v143, v86, v87
	ds_read_b64_tr_b16 v[2:3], v0 offset:25600
	ds_read_b64_tr_b16 v[4:5], v0 offset:26112
	s_waitcnt lgkmcnt(11)
	v_mfma_f32_32x32x16_bf16 v[112:127], v[180:183], v[152:155], v[112:127]
	v_cvt_pk_bf16_f32 v136, v88, v89
	v_cvt_pk_bf16_f32 v137, v90, v91
	ds_read_b64_tr_b16 v[6:7], v0 offset:29696
	ds_read_b64_tr_b16 v[8:9], v0 offset:30208
	s_waitcnt lgkmcnt(12)
	v_mfma_f32_32x32x16_bf16 v[96:111], v[176:179], v[152:155], v[96:111]
	v_cvt_pk_bf16_f32 v138, v92, v93
	v_cvt_pk_bf16_f32 v139, v94, v95
	ds_read_b64_tr_b16 v[10:11], v0 offset:26624
	ds_read_b64_tr_b16 v[12:13], v0 offset:27136
	s_waitcnt lgkmcnt(13)
	v_mfma_f32_32x32x16_bf16 v[112:127], v[172:175], v[148:151], v[112:127]
	v_cvt_pk_bf16_f32 v132, v64, v65
	v_cvt_pk_bf16_f32 v133, v66, v67
	ds_read_b64_tr_b16 v[64:65], v0 offset:30720
	ds_read_b64_tr_b16 v[66:67], v0 offset:31232
	s_waitcnt lgkmcnt(14)
	v_mfma_f32_32x32x16_bf16 v[96:111], v[168:171], v[148:151], v[96:111]
	v_cvt_pk_bf16_f32 v134, v68, v69
	v_cvt_pk_bf16_f32 v135, v70, v71
	ds_read_b64_tr_b16 v[68:69], v0 offset:27648
	ds_read_b64_tr_b16 v[70:71], v0 offset:28160
	s_waitcnt lgkmcnt(14)
	v_mfma_f32_32x32x16_bf16 v[112:127], v[164:167], v[144:147], v[112:127]
	v_cvt_pk_bf16_f32 v128, v72, v73
	v_cvt_pk_bf16_f32 v129, v74, v75
	ds_read_b64_tr_b16 v[72:73], v0 offset:31744
	ds_read_b64_tr_b16 v[74:75], v0 offset:32256
	v_mfma_f32_32x32x16_bf16 v[96:111], v[160:163], v[144:147], v[96:111]
	v_cvt_pk_bf16_f32 v130, v76, v77
	v_cvt_pk_bf16_f32 v131, v78, v79
	v_lshl_add_u64 v[14:15], v[198:199], 0, s[40:41]
	s_add_i32 s8, s87, s97
	s_mov_b32 s9, m0
	s_mov_b32 m0, s8
	s_nop 0
	global_load_lds_dwordx4 v[14:15], off
	s_mov_b32 m0, s9
	v_lshl_add_u64 v[14:15], v[196:197], 0, s[40:41]
	s_add_i32 s8, s86, s95
	s_mov_b32 s9, m0
	s_mov_b32 m0, s8
	s_nop 0
	global_load_lds_dwordx4 v[14:15], off
	s_mov_b32 m0, s9
	s_nop 1
	s_mov_b64 s[8:9], 0

.Lj1_378:
	s_add_i32 s8, s86, 0x2000
	s_cmpk_lg_i32 s86, 0x4000
	s_cselect_b32 s99, s8, 0
	v_add_u32_e32 v15, s87, v232
	ds_read_b64_tr_b16 v[160:161], v15 offset:24576
	ds_read_b64_tr_b16 v[162:163], v15 offset:25088
	s_waitcnt lgkmcnt(9)
	v_mfma_f32_32x32x16_bf16 v[80:95], v[76:79], v[156:159], v[48:63]
	v_cvt_pk_bf16_f32 v140, v112, v113
	v_cvt_pk_bf16_f32 v141, v114, v115
	ds_read_b64_tr_b16 v[112:113], v15 offset:28672
	ds_read_b64_tr_b16 v[114:115], v15 offset:29184
	s_waitcnt lgkmcnt(10)
	v_mfma_f32_32x32x16_bf16 v[64:79], v[184:187], v[156:159], v[48:63]
	v_cvt_pk_bf16_f32 v142, v116, v117
	v_cvt_pk_bf16_f32 v143, v118, v119
	ds_read_b64_tr_b16 v[2:3], v15 offset:25600
	ds_read_b64_tr_b16 v[4:5], v15 offset:26112
	s_waitcnt lgkmcnt(11)
	v_mfma_f32_32x32x16_bf16 v[80:95], v[188:191], v[152:155], v[80:95]
	v_cvt_pk_bf16_f32 v136, v120, v121
	v_cvt_pk_bf16_f32 v137, v122, v123
	ds_read_b64_tr_b16 v[6:7], v15 offset:29696
	ds_read_b64_tr_b16 v[8:9], v15 offset:30208
	s_waitcnt lgkmcnt(12)
	v_mfma_f32_32x32x16_bf16 v[64:79], v[180:183], v[152:155], v[64:79]
	v_cvt_pk_bf16_f32 v138, v124, v125
	v_cvt_pk_bf16_f32 v139, v126, v127
	ds_read_b64_tr_b16 v[10:11], v15 offset:26624
	ds_read_b64_tr_b16 v[12:13], v15 offset:27136
	s_waitcnt lgkmcnt(13)
	v_mfma_f32_32x32x16_bf16 v[80:95], v[176:179], v[148:151], v[80:95]
	v_cvt_pk_bf16_f32 v132, v96, v97
	v_cvt_pk_bf16_f32 v133, v98, v99
	ds_read_b64_tr_b16 v[96:97], v15 offset:30720
	ds_read_b64_tr_b16 v[98:99], v15 offset:31232
	s_waitcnt lgkmcnt(14)
	v_mfma_f32_32x32x16_bf16 v[64:79], v[172:175], v[148:151], v[64:79]
	v_cvt_pk_bf16_f32 v134, v100, v101
	v_cvt_pk_bf16_f32 v135, v102, v103
	ds_read_b64_tr_b16 v[100:101], v15 offset:27648
	ds_read_b64_tr_b16 v[102:103], v15 offset:28160
	s_waitcnt lgkmcnt(14)
	v_mfma_f32_32x32x16_bf16 v[80:95], v[168:171], v[144:147], v[80:95]
	v_cvt_pk_bf16_f32 v128, v104, v105
	v_cvt_pk_bf16_f32 v129, v106, v107
	ds_read_b64_tr_b16 v[104:105], v15 offset:31744
	ds_read_b64_tr_b16 v[106:107], v15 offset:32256
	v_mfma_f32_32x32x16_bf16 v[64:79], v[164:167], v[144:147], v[64:79]
	v_cvt_pk_bf16_f32 v130, v108, v109
	v_cvt_pk_bf16_f32 v131, v110, v111
	s_nop 3
	s_nop 1
	s_add_i32 s8, s86, s97
	s_mov_b32 s9, m0
	s_mov_b32 m0, s8
	s_nop 0
	global_load_lds_dwordx4 v[198:199], off
	s_mov_b32 m0, s9
	s_add_i32 s8, s99, s95
	s_mov_b32 s9, m0
	s_mov_b32 m0, s8
	s_nop 0
	global_load_lds_dwordx4 v[196:197], off
	s_mov_b32 m0, s9
	s_mov_b64 s[8:9], 0

; #define WAIT_BAR(N) asm volatile("s_waitcnt vmcnt(" #N ") lgkmcnt(0)\n\ts_barrier":::"memory")
;   #define RESC() do{ if(resc){ asm volatile("s_waitcnt lgkmcnt(0)":::"memory"); \
;       _Pragma("unroll") for(int d_=0;d_<2;++d_) _Pragma("unroll") for(int r=0;r<16;++r)o[d_][r]*=wsf[crow(r,hi)]; } }while(0)
;   #define ROT() do{sl_prev=sl_cur;sl_cur=sl_next;sl_next=(sl_next==(NSLOT-1)*SLOTB)?0:sl_next+SLOTB;}while(0)
; template<int THRL> __device__ __forceinline__ void attn_unit(int b,int qb,const bf16*Q,const bf16*__restrict__ K,const bf16*__restrict__ V,bf16*O,const __attribute__((address_space(3))) float*tab,char*shm){
;     ...
;   for(;t+7<NT;t+=2){
;     STEP(pB0,pB1,pA0,pA1,t,true,true,true);     WAIT_BAR(2); RESC(); ROT();
;     STEP(pA0,pA1,pB0,pB1,t+1,true,true,true);   WAIT_BAR(2); RESC(); ROT();
;   }
.Lj1_381:
	s_add_i32 s8, s99, 0x2000
	s_cmpk_lg_i32 s99, 0x4000
	s_cselect_b32 s96, s8, 0
	s_add_i32 s8, s12, 2
	v_lshl_add_u64 v[196:197], v[196:197], 0, s[34:35]
	s_cmp_ge_u32 s8, s66
	v_lshl_add_u64 v[198:199], v[198:199], 0, s[34:35]
	s_cbranch_scc1 .LBB0_396
	s_mov_b32 s12, s8
	s_mov_b32 s8, s86
	s_mov_b32 s87, s99
	s_mov_b32 s86, s96
	s_branch .Lj1_375
.LBB0_389:
	v_mov_b32_e32 v14, v1
	v_mov_b32_e32 v15, v1
	v_mov_b32_e32 v0, v1
	v_mov_b32_e32 v2, v1
	v_mov_b32_e32 v3, v1
	v_mov_b32_e32 v4, v1
	v_mov_b32_e32 v5, v1
	v_mov_b32_e32 v6, v1
	v_mov_b32_e32 v7, v1
	v_mov_b32_e32 v8, v1
	v_mov_b32_e32 v9, v1
	v_mov_b32_e32 v10, v1
	v_mov_b32_e32 v11, v1
	v_mov_b32_e32 v12, v1
	v_mov_b32_e32 v13, v1
	v_mov_b64_e32 v[30:31], v[14:15]
	v_mov_b64_e32 v[46:47], v[14:15]
	s_movk_i32 s96, 0x4000
	s_movk_i32 s99, 0x2000
	v_mov_b32_e32 v234, 0
	v_mov_b64_e32 v[28:29], v[12:13]
	v_mov_b64_e32 v[26:27], v[10:11]
	v_mov_b64_e32 v[24:25], v[8:9]
	v_mov_b64_e32 v[22:23], v[6:7]
	v_mov_b64_e32 v[20:21], v[4:5]
	v_mov_b64_e32 v[18:19], v[2:3]
	v_mov_b64_e32 v[16:17], v[0:1]
	v_mov_b64_e32 v[44:45], v[12:13]
	v_mov_b64_e32 v[42:43], v[10:11]
	v_mov_b64_e32 v[40:41], v[8:9]
	v_mov_b64_e32 v[38:39], v[6:7]
	v_mov_b64_e32 v[36:37], v[4:5]
	v_mov_b64_e32 v[34:35], v[2:3]
	v_mov_b64_e32 v[32:33], v[0:1]
	s_add_i32 s6, s12, 1
	s_cmp_ge_u32 s6, s66
	s_cbranch_scc0 .LBB0_397

; #define SBAR() __builtin_amdgcn_sched_barrier(0)
;   #define RESC() do{ if(resc){ asm volatile("s_waitcnt lgkmcnt(0)":::"memory"); \
;       _Pragma("unroll") for(int d_=0;d_<2;++d_) _Pragma("unroll") for(int r=0;r<16;++r)o[d_][r]*=wsf[crow(r,hi)]; } }while(0)
;   #define PKW(P,B) cvtpk_s(P[B],P[B+1])
; template<int THRL> __device__ __forceinline__ void attn_unit(int b,int qb,const bf16*Q,const bf16*__restrict__ K,const bf16*__restrict__ V,bf16*O,const __attribute__((address_space(3))) float*tab,char*shm){
;     ...
;   STEP(pB0,pB1,pA0,pA1,NT-1,false,false,false); RESC();
;   { float sacc=pB0[0]+pB0[1]; _Pragma("unroll") for(int r=2;r<16;++r)sacc+=pB0[r]; _Pragma("unroll") for(int r=0;r<16;++r)sacc+=pB1[r]; l_reg+=sacc;
;     pw0=(u32x4){PKW(pB0,0),PKW(pB0,2),PKW(pB0,4),PKW(pB0,6)};pw1=(u32x4){PKW(pB0,8),PKW(pB0,10),PKW(pB0,12),PKW(pB0,14)};pw2=(u32x4){PKW(pB1,0),PKW(pB1,2),PKW(pB1,4),PKW(pB1,6)};pw3=(u32x4){PKW(pB1,8),PKW(pB1,10),PKW(pB1,12),PKW(pB1,14)};
;     SBAR(); pv(o,vb0+sl_cur,PAF(0),PAF(1),PAF(2),PAF(3)); }
;     ...
;   {auto rr=__builtin_amdgcn_permlane32_swap(__float_as_uint(l_reg),__float_as_uint(l_reg),false,false);l_reg=__uint_as_float(rr[0])+__uint_as_float(rr[1]);}
;   if(hi==0)wsf[32+r32]=l_reg;asm volatile("s_waitcnt lgkmcnt(0)":::"memory");
.LBB0_394:
	v_add_f32_e32 v4, v96, v97
	v_add_f32_e32 v4, v98, v4
	v_add_f32_e32 v4, v99, v4
	v_add_f32_e32 v4, v100, v4
	v_add_f32_e32 v4, v101, v4
	v_add_f32_e32 v4, v102, v4
	v_add_f32_e32 v4, v103, v4
	v_add_f32_e32 v4, v104, v4
	v_add_f32_e32 v4, v105, v4
	v_add_f32_e32 v4, v106, v4
	v_add_f32_e32 v4, v107, v4
	v_add_f32_e32 v4, v108, v4
	v_add_f32_e32 v4, v109, v4
	v_add_f32_e32 v4, v110, v4
	v_add_f32_e32 v4, v111, v4
	v_add_f32_e32 v4, v48, v4
	v_add_f32_e32 v4, v49, v4
	v_add_f32_e32 v4, v50, v4
	v_add_f32_e32 v4, v51, v4
	v_add_f32_e32 v4, v52, v4
	v_add_f32_e32 v4, v53, v4
	v_add_f32_e32 v4, v54, v4
	v_add_f32_e32 v4, v55, v4
	v_add_f32_e32 v4, v56, v4
	v_add_f32_e32 v4, v57, v4
	v_add_f32_e32 v4, v58, v4
	v_add_f32_e32 v4, v59, v4
	v_add_f32_e32 v4, v60, v4
	s_cmp_lg_u32 0, -1
	v_add_f32_e32 v4, v61, v4
	s_cselect_b32 s6, 0, 0
	v_add_f32_e32 v4, v62, v4
	s_addk_i32 s6, 0x6000
	v_add_f32_e32 v4, v63, v4
	v_add3_u32 v3, v227, s6, v224
	v_add_f32_e32 v0, v0, v4
	v_cvt_pk_bf16_f32 v4, v96, v97
	v_cvt_pk_bf16_f32 v5, v98, v99
	v_cvt_pk_bf16_f32 v6, v100, v101
	v_cvt_pk_bf16_f32 v7, v102, v103
	v_cvt_pk_bf16_f32 v8, v104, v105
	v_cvt_pk_bf16_f32 v9, v106, v107
	v_cvt_pk_bf16_f32 v10, v108, v109
	v_cvt_pk_bf16_f32 v11, v110, v111
	v_cvt_pk_bf16_f32 v12, v48, v49
	v_cvt_pk_bf16_f32 v13, v50, v51
	v_cvt_pk_bf16_f32 v14, v52, v53
	v_cvt_pk_bf16_f32 v15, v54, v55
	v_cvt_pk_bf16_f32 v48, v56, v57
	v_cvt_pk_bf16_f32 v49, v58, v59
	v_cvt_pk_bf16_f32 v50, v60, v61
	v_cvt_pk_bf16_f32 v51, v62, v63
	v_add3_u32 v3, v3, v226, s99
	ds_read_b64_tr_b16 v[52:53],v3 offset:0
	ds_read_b64_tr_b16 v[54:55],v3 offset:512
	ds_read_b64_tr_b16 v[56:57],v3 offset:1024
	ds_read_b64_tr_b16 v[58:59],v3 offset:1536
	ds_read_b64_tr_b16 v[60:61],v3 offset:2048
	ds_read_b64_tr_b16 v[62:63],v3 offset:2560
	ds_read_b64_tr_b16 v[64:65],v3 offset:3072
	ds_read_b64_tr_b16 v[66:67],v3 offset:3584
	s_waitcnt lgkmcnt(0)
	s_nop 0
	v_mfma_f32_32x32x16_bf16 v[32:47], v[4:7], v[52:55], v[32:47]
	ds_read_b64_tr_b16 v[52:53],v3 offset:4096
	ds_read_b64_tr_b16 v[54:55],v3 offset:4608
	v_mfma_f32_32x32x16_bf16 v[32:47], v[8:11], v[56:59], v[32:47]
	ds_read_b64_tr_b16 v[56:57],v3 offset:5120
	ds_read_b64_tr_b16 v[58:59],v3 offset:5632
	v_mfma_f32_32x32x16_bf16 v[32:47], v[12:15], v[60:63], v[32:47]
	ds_read_b64_tr_b16 v[60:61],v3 offset:6144
	ds_read_b64_tr_b16 v[62:63],v3 offset:6656
	v_mfma_f32_32x32x16_bf16 v[32:47], v[48:51], v[64:67], v[32:47]
	ds_read_b64_tr_b16 v[64:65],v3 offset:7168
	ds_read_b64_tr_b16 v[66:67],v3 offset:7680
	s_waitcnt lgkmcnt(0)
	v_mfma_f32_32x32x16_bf16 v[16:31], v[4:7], v[52:55], v[16:31]
	v_mov_b32_e32 v238, v229
	v_mov_b32_e32 v3, v0
	s_nop 1
	v_permlane32_swap_b32_e32 v0, v3
	v_cmp_gt_u32_e32 vcc, 32, v220
	v_mfma_f32_32x32x16_bf16 v[16:31], v[8:11], v[56:59], v[16:31]
	v_mfma_f32_32x32x16_bf16 v[16:31], v[12:15], v[60:63], v[16:31]
	v_mfma_f32_32x32x16_bf16 v[16:31], v[48:51], v[64:67], v[16:31]
	s_and_saveexec_b64 s[6:7], vcc
	s_cbranch_execz .LBB0_370
	v_add_f32_e32 v0, v0, v3
	s_bitcmp1_b32 s46, 0
	s_cbranch_scc0 .Lj0_l
	v_mov_b32_e32 v0, v239
.Lj0_l:
	v_mov_b32_e32 v239, v0
	ds_write_b32 v228, v0 offset:49280
	s_branch .LBB0_370
